# grid barrier: XCD leader signals its XCD before its own acquire invalidate + previous edits
# baseline (speedup 1.0000x reference)
; __device__ __forceinline__ unsigned xb_add(unsigned* p, unsigned v) { return __hip_atomic_fetch_add(p, v, __ATOMIC_RELAXED, __HIP_MEMORY_SCOPE_AGENT); }
; __device__ __forceinline__ void xcd_barrier(const XcdBarrier& b) {
;     ...
;             __builtin_amdgcn_fence(__ATOMIC_ACQUIRE, "agent");
;             xb_add(&bar[XB_XGEN(b.x)], 1u);
;             asm volatile("s_waitcnt vmcnt(0)" ::: "memory");
.LBB0_808:
	s_or_b64 exec, exec, s[30:31]
	s_mov_b64 s[30:31], exec
	v_mbcnt_lo_u32_b32 v2, s30, 0
	v_mbcnt_hi_u32_b32 v2, s31, v2
	v_cmp_eq_u32_e32 vcc, 0, v2
	s_waitcnt vmcnt(0)
	s_nop 0
	s_and_saveexec_b64 s[36:37], vcc
	s_cbranch_execnz .LBB0_809
	buffer_inv sc1
	s_getpc_b64 s[98:99]

; __device__ __forceinline__ unsigned xb_add(unsigned* p, unsigned v) { return __hip_atomic_fetch_add(p, v, __ATOMIC_RELAXED, __HIP_MEMORY_SCOPE_AGENT); }
; __device__ __forceinline__ void xcd_barrier(const XcdBarrier& b) {
;     ...
;             xb_add(&bar[XB_XGEN(b.x)], 1u);
;             asm volatile("s_waitcnt vmcnt(0)" ::: "memory");
.LBB0_809:
	s_bcnt1_i32_b64 s2, s[30:31]
	v_readlane_b32 s4, v253, 47
	v_mov_b32_e32 v2, s2
	v_readlane_b32 s5, v253, 48
	s_nop 4
	global_atomic_add v195, v2, s[4:5]
	buffer_inv sc1
	s_getpc_b64 s[98:99]
